# v15 + D9 LN2 epilogue: per 16-row block the 4 residual/add loads issued together with counted waits (8 round trips instead of 32)
# speedup vs baseline: 1.0063x; 1.0063x over previous
; __device__ __forceinline__ float h2f_(unsigned short b) { return (float)__builtin_bit_cast(_Float16, b); }
;     __device__ __forceinline__ void fused(Acc& acc, const Unit& u, int wr, int wc, int fr, int fq, LAS unsigned char* lds, int wid, int lane) const {
;     ...
;             for (int m = 0; m < 4; ++m) { const size_t off = (size_t)(u.pm * BM + ai * HALF + wr * 64 + m * 16 + fr) * 1024 + col0;
; #pragma unroll
;                 for (int bj = 0; bj < 2; ++bj) { const size_t o = off + bj * HALF; const u32x4 bw = *(const u32x4*)(xb + o);
;                     f32x4 v0 = (f32x4){h2f_((unsigned short)(bw.x & 0xffffu)), h2f_((unsigned short)(bw.x >> 16)), h2f_((unsigned short)(bw.y & 0xffffu)), h2f_((unsigned short)(bw.y >> 16))} * ALPHA + acc[ai][bj][m][0] * sc;
;                     f32x4 v1 = (f32x4){h2f_((unsigned short)(bw.z & 0xffffu)), h2f_((unsigned short)(bw.z >> 16)), h2f_((unsigned short)(bw.w & 0xffffu)), h2f_((unsigned short)(bw.w >> 16))} * ALPHA + acc[ai][bj][m][1] * sc;
;                     if (add) { const u32x4 av = *(const u32x4*)(add + o);
;                         v0[0] += __uint_as_float(av.x << 16); v0[1] += __uint_as_float(av.x & 0xffff0000u); v0[2] += __uint_as_float(av.y << 16); v0[3] += __uint_as_float(av.y & 0xffff0000u);
;                         v1[0] += __uint_as_float(av.z << 16); v1[1] += __uint_as_float(av.z & 0xffff0000u); v1[2] += __uint_as_float(av.w << 16); v1[3] += __uint_as_float(av.w & 0xffff0000u); }
;                     acc[ai][bj][m][0] = v0; acc[ai][bj][m][1] = v1; }
;                 asm volatile("" : "+v"(acc[ai][0][m][0]), "+v"(acc[ai][0][m][1]), "+v"(acc[ai][1][m][0]), "+v"(acc[ai][1][m][1]));
;                 if (m & 1) asm volatile("" ::: "memory"); }
.LBB0_2256:
	s_andn2_b64 vcc, exec, s[70:71]
	s_barrier
	v_mov_b32 v2, 0
	s_cbranch_vccnz .LBB0_2298
	s_add_u32 s8, s10, 0x1d600000
	s_addc_u32 s9, s11, 0
	s_add_u32 s0, s10, 0x23600000
	s_addc_u32 s1, s11, 0
	s_lshl_b32 s2, s29, 5
	s_lshl_b32 s3, s12, 8
	v_lshrrev_b32_e32 v3, 1, v197
	v_add_u32_e32 v210, v2, v172
	s_or_b32 s2, s3, s2
	v_and_or_b32 v164, v3, 24, s2
	s_lshl_b32 s2, s27, 8
	v_add_u32_e32 v214, s51, v210
	v_add_u32_e32 v190, s2, v214
	v_ashrrev_i32_e32 v191, 31, v190
	v_ashrrev_i32_e32 v165, 31, v164
	v_lshlrev_b64 v[166:167], 10, v[190:191]
	v_lshl_add_u64 v[170:171], v[166:167], 0, v[164:165]
	v_lshlrev_b64 v[2:3], 1, v[170:171]
	v_lshl_add_u64 v[168:169], s[8:9], 0, v[2:3]
	global_load_dwordx4 v[4:7], v[168:169], off
	global_load_dwordx4 v[216:219], v2, s[0:1]
	global_load_dwordx4 v[220:223], v2, s[8:9] offset:256
	global_load_dwordx4 v[242:245], v2, s[0:1] offset:256
	s_mov_b32 s4, 0x3fd744fd
	s_mov_b32 s6, 0x3a000000
	v_and_b32_e32 v34, 63, v197
	s_waitcnt vmcnt(3)
	v_cvt_f32_f16_e32 v8, v4
	v_cvt_f32_f16_sdwa v9, v4 dst_sel:DWORD dst_unused:UNUSED_PAD src0_sel:WORD_1
	v_cvt_f32_f16_e32 v4, v5
	v_cvt_f32_f16_sdwa v5, v5 dst_sel:DWORD dst_unused:UNUSED_PAD src0_sel:WORD_1
	v_pk_mul_f32 v[8:9], v[8:9], s[4:5] op_sel_hi:[1,0]
	s_nop 0
	v_pk_fma_f32 v[8:9], v[160:161], s[6:7], v[8:9] op_sel_hi:[1,0,1]
	v_pk_mul_f32 v[4:5], v[4:5], s[4:5] op_sel_hi:[1,0]
	s_nop 0
	v_pk_fma_f32 v[10:11], v[162:163], s[6:7], v[4:5] op_sel_hi:[1,0,1]
	v_cvt_f32_f16_e32 v4, v6
	v_cvt_f32_f16_sdwa v5, v6 dst_sel:DWORD dst_unused:UNUSED_PAD src0_sel:WORD_1
	v_cvt_f32_f16_e32 v6, v7
	v_cvt_f32_f16_sdwa v7, v7 dst_sel:DWORD dst_unused:UNUSED_PAD src0_sel:WORD_1
	v_pk_mul_f32 v[4:5], v[4:5], s[4:5] op_sel_hi:[1,0]
	s_nop 0
	v_pk_fma_f32 v[14:15], v[156:157], s[6:7], v[4:5] op_sel_hi:[1,0,1]
	v_pk_mul_f32 v[6:7], v[6:7], s[4:5] op_sel_hi:[1,0]
	v_lshl_add_u64 v[4:5], s[0:1], 0, v[2:3]
	v_pk_fma_f32 v[12:13], v[158:159], s[6:7], v[6:7] op_sel_hi:[1,0,1]
	v_or_b32_e32 v2, 0x100, v2
	s_waitcnt vmcnt(2)
	v_lshlrev_b32_e32 v16, 16, v216
	v_and_b32_e32 v17, 0xffff0000, v216
	v_lshlrev_b32_e32 v4, 16, v217
	v_and_b32_e32 v5, 0xffff0000, v217
	v_pk_add_f32 v[20:21], v[10:11], v[4:5]
	v_lshlrev_b32_e32 v4, 16, v218
	v_and_b32_e32 v5, 0xffff0000, v218
	v_pk_add_f32 v[22:23], v[14:15], v[4:5]
	v_lshlrev_b32_e32 v4, 16, v219
	v_and_b32_e32 v5, 0xffff0000, v219
	v_pk_add_f32 v[24:25], v[12:13], v[4:5]
	v_lshl_add_u64 v[4:5], s[8:9], 0, v[2:3]
	v_pk_add_f32 v[18:19], v[8:9], v[16:17]
	v_lshl_add_u64 v[2:3], s[0:1], 0, v[2:3]
	s_waitcnt vmcnt(1)
	v_cvt_f32_f16_e32 v8, v220
	v_cvt_f32_f16_sdwa v9, v220 dst_sel:DWORD dst_unused:UNUSED_PAD src0_sel:WORD_1
	v_cvt_f32_f16_e32 v4, v221
	v_cvt_f32_f16_sdwa v5, v221 dst_sel:DWORD dst_unused:UNUSED_PAD src0_sel:WORD_1
	v_pk_mul_f32 v[8:9], v[8:9], s[4:5] op_sel_hi:[1,0]
	s_nop 0
	v_pk_fma_f32 v[8:9], v[152:153], s[6:7], v[8:9] op_sel_hi:[1,0,1]
	v_pk_mul_f32 v[4:5], v[4:5], s[4:5] op_sel_hi:[1,0]
	s_nop 0
	v_pk_fma_f32 v[10:11], v[154:155], s[6:7], v[4:5] op_sel_hi:[1,0,1]
	v_cvt_f32_f16_e32 v4, v222
	v_cvt_f32_f16_sdwa v5, v222 dst_sel:DWORD dst_unused:UNUSED_PAD src0_sel:WORD_1
	v_cvt_f32_f16_e32 v6, v223
	v_cvt_f32_f16_sdwa v7, v223 dst_sel:DWORD dst_unused:UNUSED_PAD src0_sel:WORD_1
	v_pk_mul_f32 v[4:5], v[4:5], s[4:5] op_sel_hi:[1,0]
	s_nop 0
	v_pk_fma_f32 v[14:15], v[148:149], s[6:7], v[4:5] op_sel_hi:[1,0,1]
	v_pk_mul_f32 v[6:7], v[6:7], s[4:5] op_sel_hi:[1,0]
	s_nop 0
	v_pk_fma_f32 v[12:13], v[150:151], s[6:7], v[6:7] op_sel_hi:[1,0,1]
	s_waitcnt vmcnt(0)
	v_lshlrev_b32_e32 v6, 16, v242
	v_and_b32_e32 v7, 0xffff0000, v242
	v_lshlrev_b32_e32 v2, 16, v243
	v_and_b32_e32 v3, 0xffff0000, v243
	v_pk_add_f32 v[6:7], v[8:9], v[6:7]
	v_pk_add_f32 v[8:9], v[10:11], v[2:3]
	v_add_u32_e32 v10, 16, v190
	v_ashrrev_i32_e32 v11, 31, v10
	v_lshlrev_b64 v[152:153], 10, v[10:11]
	v_lshl_add_u64 v[148:149], v[152:153], 0, v[164:165]
	v_lshlrev_b32_e32 v2, 16, v244
	v_and_b32_e32 v3, 0xffff0000, v244
	v_lshlrev_b32_e32 v4, 16, v245
	v_and_b32_e32 v5, 0xffff0000, v245
	v_lshlrev_b64 v[10:11], 1, v[148:149]
	v_pk_add_f32 v[2:3], v[14:15], v[2:3]
	v_pk_add_f32 v[4:5], v[12:13], v[4:5]
	v_lshl_add_u64 v[156:157], s[8:9], 0, v[10:11]
	global_load_dwordx4 v[12:15], v[156:157], off
	global_load_dwordx4 v[216:219], v10, s[0:1]
	global_load_dwordx4 v[220:223], v10, s[8:9] offset:256
	global_load_dwordx4 v[242:245], v10, s[0:1] offset:256
	s_waitcnt vmcnt(3)
	v_cvt_f32_f16_e32 v16, v12
	v_cvt_f32_f16_sdwa v17, v12 dst_sel:DWORD dst_unused:UNUSED_PAD src0_sel:WORD_1
	v_cvt_f32_f16_e32 v12, v13
	v_cvt_f32_f16_sdwa v13, v13 dst_sel:DWORD dst_unused:UNUSED_PAD src0_sel:WORD_1
	v_pk_mul_f32 v[16:17], v[16:17], s[4:5] op_sel_hi:[1,0]
	s_nop 0
	v_pk_fma_f32 v[16:17], v[40:41], s[6:7], v[16:17] op_sel_hi:[1,0,1]
	v_pk_mul_f32 v[12:13], v[12:13], s[4:5] op_sel_hi:[1,0]
	s_nop 0
	v_pk_fma_f32 v[26:27], v[42:43], s[6:7], v[12:13] op_sel_hi:[1,0,1]
	v_cvt_f32_f16_e32 v12, v14
	v_cvt_f32_f16_sdwa v13, v14 dst_sel:DWORD dst_unused:UNUSED_PAD src0_sel:WORD_1
	v_cvt_f32_f16_e32 v14, v15
	v_cvt_f32_f16_sdwa v15, v15 dst_sel:DWORD dst_unused:UNUSED_PAD src0_sel:WORD_1
	v_pk_mul_f32 v[12:13], v[12:13], s[4:5] op_sel_hi:[1,0]
	s_nop 0
	v_pk_fma_f32 v[30:31], v[36:37], s[6:7], v[12:13] op_sel_hi:[1,0,1]
	v_pk_mul_f32 v[14:15], v[14:15], s[4:5] op_sel_hi:[1,0]
	v_lshl_add_u64 v[12:13], s[0:1], 0, v[10:11]
	v_pk_fma_f32 v[28:29], v[38:39], s[6:7], v[14:15] op_sel_hi:[1,0,1]
	v_or_b32_e32 v10, 0x100, v10
	s_waitcnt vmcnt(2)
; __device__ __forceinline__ float h2f_(unsigned short b) { return (float)__builtin_bit_cast(_Float16, b); }
;     __device__ __forceinline__ void fused(Acc& acc, const Unit& u, int wr, int wc, int fr, int fq, LAS unsigned char* lds, int wid, int lane) const {
;     ...
;             for (int m = 0; m < 4; ++m) { const size_t off = (size_t)(u.pm * BM + ai * HALF + wr * 64 + m * 16 + fr) * 1024 + col0;
; #pragma unroll
;                 for (int bj = 0; bj < 2; ++bj) { const size_t o = off + bj * HALF; const u32x4 bw = *(const u32x4*)(xb + o);
;                     f32x4 v0 = (f32x4){h2f_((unsigned short)(bw.x & 0xffffu)), h2f_((unsigned short)(bw.x >> 16)), h2f_((unsigned short)(bw.y & 0xffffu)), h2f_((unsigned short)(bw.y >> 16))} * ALPHA + acc[ai][bj][m][0] * sc;
;                     f32x4 v1 = (f32x4){h2f_((unsigned short)(bw.z & 0xffffu)), h2f_((unsigned short)(bw.z >> 16)), h2f_((unsigned short)(bw.w & 0xffffu)), h2f_((unsigned short)(bw.w >> 16))} * ALPHA + acc[ai][bj][m][1] * sc;
;                     if (add) { const u32x4 av = *(const u32x4*)(add + o);
;                         v0[0] += __uint_as_float(av.x << 16); v0[1] += __uint_as_float(av.x & 0xffff0000u); v0[2] += __uint_as_float(av.y << 16); v0[3] += __uint_as_float(av.y & 0xffff0000u);
;                         v1[0] += __uint_as_float(av.z << 16); v1[1] += __uint_as_float(av.z & 0xffff0000u); v1[2] += __uint_as_float(av.w << 16); v1[3] += __uint_as_float(av.w & 0xffff0000u); }
;                     acc[ai][bj][m][0] = v0; acc[ai][bj][m][1] = v1; }
;                 asm volatile("" : "+v"(acc[ai][0][m][0]), "+v"(acc[ai][0][m][1]), "+v"(acc[ai][1][m][0]), "+v"(acc[ai][1][m][1]));
;                 if (m & 1) asm volatile("" ::: "memory"); }
	v_lshlrev_b32_e32 v32, 16, v216
	v_and_b32_e32 v33, 0xffff0000, v216
	v_lshlrev_b32_e32 v12, 16, v217
	v_and_b32_e32 v13, 0xffff0000, v217
	v_pk_add_f32 v[38:39], v[26:27], v[12:13]
	v_lshlrev_b32_e32 v12, 16, v218
	v_and_b32_e32 v13, 0xffff0000, v218
	v_pk_add_f32 v[40:41], v[30:31], v[12:13]
	v_lshlrev_b32_e32 v12, 16, v219
	v_and_b32_e32 v13, 0xffff0000, v219
	v_pk_add_f32 v[42:43], v[28:29], v[12:13]
	v_lshl_add_u64 v[12:13], s[8:9], 0, v[10:11]
	v_pk_add_f32 v[36:37], v[16:17], v[32:33]
	v_lshl_add_u64 v[10:11], s[0:1], 0, v[10:11]
	s_waitcnt vmcnt(1)
	v_cvt_f32_f16_e32 v16, v220
	v_cvt_f32_f16_sdwa v17, v220 dst_sel:DWORD dst_unused:UNUSED_PAD src0_sel:WORD_1
	v_cvt_f32_f16_e32 v12, v221
	v_cvt_f32_f16_sdwa v13, v221 dst_sel:DWORD dst_unused:UNUSED_PAD src0_sel:WORD_1
	v_pk_mul_f32 v[16:17], v[16:17], s[4:5] op_sel_hi:[1,0]
	s_nop 0
	v_pk_fma_f32 v[16:17], v[144:145], s[6:7], v[16:17] op_sel_hi:[1,0,1]
	v_pk_mul_f32 v[12:13], v[12:13], s[4:5] op_sel_hi:[1,0]
	s_nop 0
	v_pk_fma_f32 v[26:27], v[146:147], s[6:7], v[12:13] op_sel_hi:[1,0,1]
	v_cvt_f32_f16_e32 v12, v222
	v_cvt_f32_f16_sdwa v13, v222 dst_sel:DWORD dst_unused:UNUSED_PAD src0_sel:WORD_1
	v_cvt_f32_f16_e32 v14, v223
	v_cvt_f32_f16_sdwa v15, v223 dst_sel:DWORD dst_unused:UNUSED_PAD src0_sel:WORD_1
	v_pk_mul_f32 v[12:13], v[12:13], s[4:5] op_sel_hi:[1,0]
	s_nop 0
	v_pk_fma_f32 v[30:31], v[140:141], s[6:7], v[12:13] op_sel_hi:[1,0,1]
	v_pk_mul_f32 v[14:15], v[14:15], s[4:5] op_sel_hi:[1,0]
	v_add_f32_e32 v141, v8, v9
	v_pk_fma_f32 v[28:29], v[142:143], s[6:7], v[14:15] op_sel_hi:[1,0,1]
	v_mov_b32_e32 v140, v3
	s_waitcnt vmcnt(0)
	v_lshlrev_b32_e32 v14, 16, v242
	v_and_b32_e32 v15, 0xffff0000, v242
	v_lshlrev_b32_e32 v10, 16, v243
	v_and_b32_e32 v11, 0xffff0000, v243
	v_pk_add_f32 v[14:15], v[16:17], v[14:15]
	v_pk_add_f32 v[16:17], v[26:27], v[10:11]
	v_add_u32_e32 v26, 32, v190
	v_ashrrev_i32_e32 v27, 31, v26
	v_lshlrev_b64 v[154:155], 10, v[26:27]
	v_lshlrev_b32_e32 v10, 16, v244
	v_and_b32_e32 v11, 0xffff0000, v244
	v_lshlrev_b32_e32 v12, 16, v245
	v_and_b32_e32 v13, 0xffff0000, v245
	v_lshl_add_u64 v[160:161], v[154:155], 0, v[164:165]
	v_pk_add_f32 v[10:11], v[30:31], v[10:11]
	v_pk_add_f32 v[12:13], v[28:29], v[12:13]
	v_lshlrev_b64 v[26:27], 1, v[160:161]
	v_lshl_add_u64 v[162:163], s[8:9], 0, v[26:27]
	global_load_dwordx4 v[28:31], v[162:163], off
	global_load_dwordx4 v[216:219], v26, s[0:1]
	global_load_dwordx4 v[220:223], v26, s[8:9] offset:256
	global_load_dwordx4 v[242:245], v26, s[0:1] offset:256
	s_waitcnt vmcnt(3)
	v_cvt_f32_f16_e32 v32, v28
	v_cvt_f32_f16_sdwa v33, v28 dst_sel:DWORD dst_unused:UNUSED_PAD src0_sel:WORD_1
	v_cvt_f32_f16_e32 v28, v29
	v_cvt_f32_f16_sdwa v29, v29 dst_sel:DWORD dst_unused:UNUSED_PAD src0_sel:WORD_1
	v_pk_mul_f32 v[32:33], v[32:33], s[4:5] op_sel_hi:[1,0]
	s_nop 0
	v_pk_fma_f32 v[32:33], v[56:57], s[6:7], v[32:33] op_sel_hi:[1,0,1]
	v_pk_mul_f32 v[28:29], v[28:29], s[4:5] op_sel_hi:[1,0]
	s_nop 0
	v_pk_fma_f32 v[58:59], v[58:59], s[6:7], v[28:29] op_sel_hi:[1,0,1]
	v_cvt_f32_f16_e32 v28, v30
	v_cvt_f32_f16_sdwa v29, v30 dst_sel:DWORD dst_unused:UNUSED_PAD src0_sel:WORD_1
	v_cvt_f32_f16_e32 v30, v31
	v_cvt_f32_f16_sdwa v31, v31 dst_sel:DWORD dst_unused:UNUSED_PAD src0_sel:WORD_1
	v_pk_mul_f32 v[28:29], v[28:29], s[4:5] op_sel_hi:[1,0]
	s_nop 0
	v_pk_fma_f32 v[52:53], v[52:53], s[6:7], v[28:29] op_sel_hi:[1,0,1]
	v_pk_mul_f32 v[30:31], v[30:31], s[4:5] op_sel_hi:[1,0]
	v_lshl_add_u64 v[28:29], s[0:1], 0, v[26:27]
	v_pk_fma_f32 v[54:55], v[54:55], s[6:7], v[30:31] op_sel_hi:[1,0,1]
	v_or_b32_e32 v26, 0x100, v26
	s_waitcnt vmcnt(2)
	v_lshlrev_b32_e32 v56, 16, v216
	v_and_b32_e32 v57, 0xffff0000, v216
	v_lshlrev_b32_e32 v28, 16, v217
	v_and_b32_e32 v29, 0xffff0000, v217
	v_pk_add_f32 v[58:59], v[58:59], v[28:29]
	v_lshlrev_b32_e32 v28, 16, v218
	v_and_b32_e32 v29, 0xffff0000, v218
	v_pk_add_f32 v[52:53], v[52:53], v[28:29]
	v_lshlrev_b32_e32 v28, 16, v219
	v_and_b32_e32 v29, 0xffff0000, v219
	v_pk_add_f32 v[54:55], v[54:55], v[28:29]
	v_lshl_add_u64 v[28:29], s[8:9], 0, v[26:27]
	v_pk_add_f32 v[56:57], v[32:33], v[56:57]
	v_lshl_add_u64 v[26:27], s[0:1], 0, v[26:27]
	s_waitcnt vmcnt(1)
	v_cvt_f32_f16_e32 v32, v220
	v_cvt_f32_f16_sdwa v33, v220 dst_sel:DWORD dst_unused:UNUSED_PAD src0_sel:WORD_1
	v_cvt_f32_f16_e32 v28, v221
	v_cvt_f32_f16_sdwa v29, v221 dst_sel:DWORD dst_unused:UNUSED_PAD src0_sel:WORD_1
	v_pk_mul_f32 v[32:33], v[32:33], s[4:5] op_sel_hi:[1,0]
	s_nop 0
	v_pk_fma_f32 v[32:33], v[136:137], s[6:7], v[32:33] op_sel_hi:[1,0,1]
	v_pk_mul_f32 v[28:29], v[28:29], s[4:5] op_sel_hi:[1,0]
	s_nop 0
	v_pk_fma_f32 v[138:139], v[138:139], s[6:7], v[28:29] op_sel_hi:[1,0,1]
	v_cvt_f32_f16_e32 v28, v222
	v_cvt_f32_f16_sdwa v29, v222 dst_sel:DWORD dst_unused:UNUSED_PAD src0_sel:WORD_1
	v_cvt_f32_f16_e32 v30, v223
	v_cvt_f32_f16_sdwa v31, v223 dst_sel:DWORD dst_unused:UNUSED_PAD src0_sel:WORD_1
	v_pk_mul_f32 v[28:29], v[28:29], s[4:5] op_sel_hi:[1,0]
	s_nop 0
	v_pk_fma_f32 v[132:133], v[132:133], s[6:7], v[28:29] op_sel_hi:[1,0,1]
	v_pk_mul_f32 v[30:31], v[30:31], s[4:5] op_sel_hi:[1,0]
	s_nop 0
	v_pk_fma_f32 v[134:135], v[134:135], s[6:7], v[30:31] op_sel_hi:[1,0,1]
	s_waitcnt vmcnt(0)
; __device__ __forceinline__ float h2f_(unsigned short b) { return (float)__builtin_bit_cast(_Float16, b); }
;     __device__ __forceinline__ void fused(Acc& acc, const Unit& u, int wr, int wc, int fr, int fq, LAS unsigned char* lds, int wid, int lane) const {
;     ...
;             for (int m = 0; m < 4; ++m) { const size_t off = (size_t)(u.pm * BM + ai * HALF + wr * 64 + m * 16 + fr) * 1024 + col0;
; #pragma unroll
;                 for (int bj = 0; bj < 2; ++bj) { const size_t o = off + bj * HALF; const u32x4 bw = *(const u32x4*)(xb + o);
;                     f32x4 v0 = (f32x4){h2f_((unsigned short)(bw.x & 0xffffu)), h2f_((unsigned short)(bw.x >> 16)), h2f_((unsigned short)(bw.y & 0xffffu)), h2f_((unsigned short)(bw.y >> 16))} * ALPHA + acc[ai][bj][m][0] * sc;
;                     f32x4 v1 = (f32x4){h2f_((unsigned short)(bw.z & 0xffffu)), h2f_((unsigned short)(bw.z >> 16)), h2f_((unsigned short)(bw.w & 0xffffu)), h2f_((unsigned short)(bw.w >> 16))} * ALPHA + acc[ai][bj][m][1] * sc;
;                     if (add) { const u32x4 av = *(const u32x4*)(add + o);
;                         v0[0] += __uint_as_float(av.x << 16); v0[1] += __uint_as_float(av.x & 0xffff0000u); v0[2] += __uint_as_float(av.y << 16); v0[3] += __uint_as_float(av.y & 0xffff0000u);
;                         v1[0] += __uint_as_float(av.z << 16); v1[1] += __uint_as_float(av.z & 0xffff0000u); v1[2] += __uint_as_float(av.w << 16); v1[3] += __uint_as_float(av.w & 0xffff0000u); }
;                     acc[ai][bj][m][0] = v0; acc[ai][bj][m][1] = v1; }
;                 asm volatile("" : "+v"(acc[ai][0][m][0]), "+v"(acc[ai][0][m][1]), "+v"(acc[ai][1][m][0]), "+v"(acc[ai][1][m][1]));
;                 if (m & 1) asm volatile("" ::: "memory"); }
	v_lshlrev_b32_e32 v30, 16, v242
	v_and_b32_e32 v31, 0xffff0000, v242
	v_lshlrev_b32_e32 v26, 16, v243
	v_and_b32_e32 v27, 0xffff0000, v243
	v_pk_add_f32 v[30:31], v[32:33], v[30:31]
	v_pk_add_f32 v[32:33], v[138:139], v[26:27]
	v_lshlrev_b32_e32 v26, 16, v244
	v_and_b32_e32 v27, 0xffff0000, v244
	v_pk_add_f32 v[26:27], v[132:133], v[26:27]
	v_add_u32_e32 v132, 48, v190
	v_ashrrev_i32_e32 v133, 31, v132
	v_lshlrev_b64 v[158:159], 10, v[132:133]
	v_lshl_add_u64 v[174:175], v[158:159], 0, v[164:165]
	v_lshlrev_b32_e32 v28, 16, v245
	v_and_b32_e32 v29, 0xffff0000, v245
	v_lshlrev_b64 v[132:133], 1, v[174:175]
	v_pk_add_f32 v[28:29], v[134:135], v[28:29]
	v_lshl_add_u64 v[176:177], s[8:9], 0, v[132:133]
	global_load_dwordx4 v[134:137], v[176:177], off
	global_load_dwordx4 v[216:219], v132, s[0:1]
	global_load_dwordx4 v[220:223], v132, s[8:9] offset:256
	global_load_dwordx4 v[242:245], v132, s[0:1] offset:256
	s_waitcnt vmcnt(3)
	v_cvt_f32_f16_e32 v138, v134
	v_cvt_f32_f16_sdwa v139, v134 dst_sel:DWORD dst_unused:UNUSED_PAD src0_sel:WORD_1
	v_cvt_f32_f16_e32 v134, v135
	v_cvt_f32_f16_sdwa v135, v135 dst_sel:DWORD dst_unused:UNUSED_PAD src0_sel:WORD_1
	v_pk_mul_f32 v[138:139], v[138:139], s[4:5] op_sel_hi:[1,0]
	s_nop 0
	v_pk_fma_f32 v[72:73], v[72:73], s[6:7], v[138:139] op_sel_hi:[1,0,1]
	v_pk_mul_f32 v[134:135], v[134:135], s[4:5] op_sel_hi:[1,0]
	s_nop 0
	v_pk_fma_f32 v[74:75], v[74:75], s[6:7], v[134:135] op_sel_hi:[1,0,1]
	v_cvt_f32_f16_e32 v134, v136
	v_cvt_f32_f16_sdwa v135, v136 dst_sel:DWORD dst_unused:UNUSED_PAD src0_sel:WORD_1
	v_cvt_f32_f16_e32 v136, v137
	v_cvt_f32_f16_sdwa v137, v137 dst_sel:DWORD dst_unused:UNUSED_PAD src0_sel:WORD_1
	v_pk_mul_f32 v[134:135], v[134:135], s[4:5] op_sel_hi:[1,0]
	s_nop 0
	v_pk_fma_f32 v[134:135], v[68:69], s[6:7], v[134:135] op_sel_hi:[1,0,1]
	v_pk_mul_f32 v[136:137], v[136:137], s[4:5] op_sel_hi:[1,0]
	v_lshl_add_u64 v[68:69], s[0:1], 0, v[132:133]
	v_pk_fma_f32 v[136:137], v[70:71], s[6:7], v[136:137] op_sel_hi:[1,0,1]
	v_or_b32_e32 v132, 0x100, v132
	s_waitcnt vmcnt(2)
	v_lshlrev_b32_e32 v138, 16, v216
	v_and_b32_e32 v139, 0xffff0000, v216
	v_lshlrev_b32_e32 v68, 16, v217
	v_and_b32_e32 v69, 0xffff0000, v217
	v_pk_add_f32 v[74:75], v[74:75], v[68:69]
	v_lshlrev_b32_e32 v68, 16, v218
	v_and_b32_e32 v69, 0xffff0000, v218
	v_pk_add_f32 v[68:69], v[134:135], v[68:69]
	v_lshlrev_b32_e32 v70, 16, v219
	v_and_b32_e32 v71, 0xffff0000, v219
	v_lshl_add_u64 v[134:135], s[8:9], 0, v[132:133]
	v_pk_add_f32 v[70:71], v[136:137], v[70:71]
	v_pk_add_f32 v[72:73], v[72:73], v[138:139]
	s_waitcnt vmcnt(1)
	v_cvt_f32_f16_e32 v138, v220
	v_cvt_f32_f16_sdwa v139, v220 dst_sel:DWORD dst_unused:UNUSED_PAD src0_sel:WORD_1
	v_cvt_f32_f16_e32 v134, v221
	v_cvt_f32_f16_sdwa v135, v221 dst_sel:DWORD dst_unused:UNUSED_PAD src0_sel:WORD_1
	v_pk_mul_f32 v[138:139], v[138:139], s[4:5] op_sel_hi:[1,0]
	s_nop 0
	v_pk_fma_f32 v[48:49], v[48:49], s[6:7], v[138:139] op_sel_hi:[1,0,1]
	v_pk_mul_f32 v[134:135], v[134:135], s[4:5] op_sel_hi:[1,0]
	s_nop 0
	v_pk_fma_f32 v[50:51], v[50:51], s[6:7], v[134:135] op_sel_hi:[1,0,1]
	v_cvt_f32_f16_e32 v134, v222
	v_cvt_f32_f16_sdwa v135, v222 dst_sel:DWORD dst_unused:UNUSED_PAD src0_sel:WORD_1
	v_cvt_f32_f16_e32 v136, v223
	v_cvt_f32_f16_sdwa v137, v223 dst_sel:DWORD dst_unused:UNUSED_PAD src0_sel:WORD_1
	v_pk_mul_f32 v[134:135], v[134:135], s[4:5] op_sel_hi:[1,0]
	s_nop 0
	v_pk_fma_f32 v[134:135], v[44:45], s[6:7], v[134:135] op_sel_hi:[1,0,1]
	v_pk_mul_f32 v[136:137], v[136:137], s[4:5] op_sel_hi:[1,0]
	v_lshl_add_u64 v[44:45], s[0:1], 0, v[132:133]
	v_pk_fma_f32 v[136:137], v[46:47], s[6:7], v[136:137] op_sel_hi:[1,0,1]
	s_waitcnt vmcnt(0)
	v_lshlrev_b32_e32 v132, 16, v242
	v_and_b32_e32 v133, 0xffff0000, v242
	v_pk_add_f32 v[48:49], v[48:49], v[132:133]
	v_add_u32_e32 v132, 0x80, v190
	v_ashrrev_i32_e32 v133, 31, v132
	v_lshlrev_b32_e32 v44, 16, v243
	v_and_b32_e32 v45, 0xffff0000, v243
	v_lshlrev_b64 v[172:173], 10, v[132:133]
	v_pk_add_f32 v[50:51], v[50:51], v[44:45]
	v_lshlrev_b32_e32 v44, 16, v244
	v_and_b32_e32 v45, 0xffff0000, v244
	v_lshlrev_b32_e32 v46, 16, v245
	v_and_b32_e32 v47, 0xffff0000, v245
	v_lshl_add_u64 v[180:181], v[172:173], 0, v[164:165]
	v_pk_add_f32 v[44:45], v[134:135], v[44:45]
	v_pk_add_f32 v[46:47], v[136:137], v[46:47]
	v_lshlrev_b64 v[132:133], 1, v[180:181]
	v_lshl_add_u64 v[182:183], s[8:9], 0, v[132:133]
	global_load_dwordx4 v[134:137], v[182:183], off
	global_load_dwordx4 v[216:219], v132, s[0:1]
	global_load_dwordx4 v[220:223], v132, s[8:9] offset:256
	global_load_dwordx4 v[242:245], v132, s[0:1] offset:256
	s_waitcnt vmcnt(3)
	v_cvt_f32_f16_e32 v138, v134
	v_cvt_f32_f16_sdwa v139, v134 dst_sel:DWORD dst_unused:UNUSED_PAD src0_sel:WORD_1
	v_cvt_f32_f16_e32 v134, v135
	v_cvt_f32_f16_sdwa v135, v135 dst_sel:DWORD dst_unused:UNUSED_PAD src0_sel:WORD_1
	v_pk_mul_f32 v[138:139], v[138:139], s[4:5] op_sel_hi:[1,0]
	s_nop 0
	v_pk_fma_f32 v[112:113], v[112:113], s[6:7], v[138:139] op_sel_hi:[1,0,1]
	v_pk_mul_f32 v[134:135], v[134:135], s[4:5] op_sel_hi:[1,0]
	s_nop 0
	v_pk_fma_f32 v[114:115], v[114:115], s[6:7], v[134:135] op_sel_hi:[1,0,1]
	v_cvt_f32_f16_e32 v134, v136
	v_cvt_f32_f16_sdwa v135, v136 dst_sel:DWORD dst_unused:UNUSED_PAD src0_sel:WORD_1
	v_cvt_f32_f16_e32 v136, v137
	v_cvt_f32_f16_sdwa v137, v137 dst_sel:DWORD dst_unused:UNUSED_PAD src0_sel:WORD_1
	v_pk_mul_f32 v[134:135], v[134:135], s[4:5] op_sel_hi:[1,0]
	s_nop 0
	v_pk_fma_f32 v[134:135], v[108:109], s[6:7], v[134:135] op_sel_hi:[1,0,1]
	v_pk_mul_f32 v[136:137], v[136:137], s[4:5] op_sel_hi:[1,0]
	v_lshl_add_u64 v[108:109], s[0:1], 0, v[132:133]
	v_pk_fma_f32 v[136:137], v[110:111], s[6:7], v[136:137] op_sel_hi:[1,0,1]
	v_or_b32_e32 v132, 0x100, v132
	s_waitcnt vmcnt(2)
; __device__ __forceinline__ float h2f_(unsigned short b) { return (float)__builtin_bit_cast(_Float16, b); }
;     __device__ __forceinline__ void fused(Acc& acc, const Unit& u, int wr, int wc, int fr, int fq, LAS unsigned char* lds, int wid, int lane) const {
;     ...
;             for (int m = 0; m < 4; ++m) { const size_t off = (size_t)(u.pm * BM + ai * HALF + wr * 64 + m * 16 + fr) * 1024 + col0;
; #pragma unroll
;                 for (int bj = 0; bj < 2; ++bj) { const size_t o = off + bj * HALF; const u32x4 bw = *(const u32x4*)(xb + o);
;                     f32x4 v0 = (f32x4){h2f_((unsigned short)(bw.x & 0xffffu)), h2f_((unsigned short)(bw.x >> 16)), h2f_((unsigned short)(bw.y & 0xffffu)), h2f_((unsigned short)(bw.y >> 16))} * ALPHA + acc[ai][bj][m][0] * sc;
;                     f32x4 v1 = (f32x4){h2f_((unsigned short)(bw.z & 0xffffu)), h2f_((unsigned short)(bw.z >> 16)), h2f_((unsigned short)(bw.w & 0xffffu)), h2f_((unsigned short)(bw.w >> 16))} * ALPHA + acc[ai][bj][m][1] * sc;
;                     if (add) { const u32x4 av = *(const u32x4*)(add + o);
;                         v0[0] += __uint_as_float(av.x << 16); v0[1] += __uint_as_float(av.x & 0xffff0000u); v0[2] += __uint_as_float(av.y << 16); v0[3] += __uint_as_float(av.y & 0xffff0000u);
;                         v1[0] += __uint_as_float(av.z << 16); v1[1] += __uint_as_float(av.z & 0xffff0000u); v1[2] += __uint_as_float(av.w << 16); v1[3] += __uint_as_float(av.w & 0xffff0000u); }
;                     acc[ai][bj][m][0] = v0; acc[ai][bj][m][1] = v1; }
;                 asm volatile("" : "+v"(acc[ai][0][m][0]), "+v"(acc[ai][0][m][1]), "+v"(acc[ai][1][m][0]), "+v"(acc[ai][1][m][1]));
;                 if (m & 1) asm volatile("" ::: "memory"); }
	v_lshlrev_b32_e32 v138, 16, v216
	v_and_b32_e32 v139, 0xffff0000, v216
	v_lshlrev_b32_e32 v108, 16, v217
	v_and_b32_e32 v109, 0xffff0000, v217
	v_pk_add_f32 v[114:115], v[114:115], v[108:109]
	v_lshlrev_b32_e32 v108, 16, v218
	v_and_b32_e32 v109, 0xffff0000, v218
	v_pk_add_f32 v[108:109], v[134:135], v[108:109]
	v_lshlrev_b32_e32 v110, 16, v219
	v_and_b32_e32 v111, 0xffff0000, v219
	v_lshl_add_u64 v[134:135], s[8:9], 0, v[132:133]
	v_pk_add_f32 v[110:111], v[136:137], v[110:111]
	v_pk_add_f32 v[112:113], v[112:113], v[138:139]
	s_waitcnt vmcnt(1)
	v_cvt_f32_f16_e32 v138, v220
	v_cvt_f32_f16_sdwa v139, v220 dst_sel:DWORD dst_unused:UNUSED_PAD src0_sel:WORD_1
	v_cvt_f32_f16_e32 v134, v221
	v_cvt_f32_f16_sdwa v135, v221 dst_sel:DWORD dst_unused:UNUSED_PAD src0_sel:WORD_1
	v_pk_mul_f32 v[138:139], v[138:139], s[4:5] op_sel_hi:[1,0]
	s_nop 0
	v_pk_fma_f32 v[64:65], v[64:65], s[6:7], v[138:139] op_sel_hi:[1,0,1]
	v_pk_mul_f32 v[134:135], v[134:135], s[4:5] op_sel_hi:[1,0]
	s_nop 0
	v_pk_fma_f32 v[66:67], v[66:67], s[6:7], v[134:135] op_sel_hi:[1,0,1]
	v_cvt_f32_f16_e32 v134, v222
	v_cvt_f32_f16_sdwa v135, v222 dst_sel:DWORD dst_unused:UNUSED_PAD src0_sel:WORD_1
	v_cvt_f32_f16_e32 v136, v223
	v_cvt_f32_f16_sdwa v137, v223 dst_sel:DWORD dst_unused:UNUSED_PAD src0_sel:WORD_1
	v_pk_mul_f32 v[134:135], v[134:135], s[4:5] op_sel_hi:[1,0]
	s_nop 0
	v_pk_fma_f32 v[134:135], v[60:61], s[6:7], v[134:135] op_sel_hi:[1,0,1]
	v_pk_mul_f32 v[136:137], v[136:137], s[4:5] op_sel_hi:[1,0]
	v_lshl_add_u64 v[60:61], s[0:1], 0, v[132:133]
	v_pk_fma_f32 v[136:137], v[62:63], s[6:7], v[136:137] op_sel_hi:[1,0,1]
	s_waitcnt vmcnt(0)
	v_lshlrev_b32_e32 v132, 16, v242
	v_and_b32_e32 v133, 0xffff0000, v242
	v_pk_add_f32 v[64:65], v[64:65], v[132:133]
	v_add_u32_e32 v132, 0x90, v190
	v_ashrrev_i32_e32 v133, 31, v132
	v_lshlrev_b64 v[178:179], 10, v[132:133]
	v_lshlrev_b32_e32 v60, 16, v243
	v_and_b32_e32 v61, 0xffff0000, v243
	v_lshl_add_u64 v[186:187], v[178:179], 0, v[164:165]
	v_pk_add_f32 v[66:67], v[66:67], v[60:61]
	v_lshlrev_b32_e32 v60, 16, v244
	v_and_b32_e32 v61, 0xffff0000, v244
	v_lshlrev_b32_e32 v62, 16, v245
	v_and_b32_e32 v63, 0xffff0000, v245
	v_lshlrev_b64 v[132:133], 1, v[186:187]
	v_pk_add_f32 v[60:61], v[134:135], v[60:61]
	v_pk_add_f32 v[62:63], v[136:137], v[62:63]
	v_lshl_add_u64 v[188:189], s[8:9], 0, v[132:133]
	global_load_dwordx4 v[134:137], v[188:189], off
	global_load_dwordx4 v[216:219], v132, s[0:1]
	global_load_dwordx4 v[220:223], v132, s[8:9] offset:256
	global_load_dwordx4 v[242:245], v132, s[0:1] offset:256
	s_waitcnt vmcnt(3)
	v_cvt_f32_f16_e32 v138, v134
	v_cvt_f32_f16_sdwa v139, v134 dst_sel:DWORD dst_unused:UNUSED_PAD src0_sel:WORD_1
	v_cvt_f32_f16_e32 v134, v135
	v_cvt_f32_f16_sdwa v135, v135 dst_sel:DWORD dst_unused:UNUSED_PAD src0_sel:WORD_1
	v_pk_mul_f32 v[138:139], v[138:139], s[4:5] op_sel_hi:[1,0]
	s_nop 0
	v_pk_fma_f32 v[128:129], v[128:129], s[6:7], v[138:139] op_sel_hi:[1,0,1]
	v_pk_mul_f32 v[134:135], v[134:135], s[4:5] op_sel_hi:[1,0]
	s_nop 0
	v_pk_fma_f32 v[130:131], v[130:131], s[6:7], v[134:135] op_sel_hi:[1,0,1]
	v_cvt_f32_f16_e32 v134, v136
	v_cvt_f32_f16_sdwa v135, v136 dst_sel:DWORD dst_unused:UNUSED_PAD src0_sel:WORD_1
	v_cvt_f32_f16_e32 v136, v137
	v_cvt_f32_f16_sdwa v137, v137 dst_sel:DWORD dst_unused:UNUSED_PAD src0_sel:WORD_1
	v_pk_mul_f32 v[134:135], v[134:135], s[4:5] op_sel_hi:[1,0]
	s_nop 0
	v_pk_fma_f32 v[134:135], v[124:125], s[6:7], v[134:135] op_sel_hi:[1,0,1]
	v_pk_mul_f32 v[136:137], v[136:137], s[4:5] op_sel_hi:[1,0]
	v_lshl_add_u64 v[124:125], s[0:1], 0, v[132:133]
	v_pk_fma_f32 v[136:137], v[126:127], s[6:7], v[136:137] op_sel_hi:[1,0,1]
	v_or_b32_e32 v132, 0x100, v132
	s_waitcnt vmcnt(2)
	v_lshlrev_b32_e32 v138, 16, v216
	v_and_b32_e32 v139, 0xffff0000, v216
	v_lshlrev_b32_e32 v124, 16, v217
	v_and_b32_e32 v125, 0xffff0000, v217
	v_pk_add_f32 v[130:131], v[130:131], v[124:125]
	v_lshlrev_b32_e32 v124, 16, v218
	v_and_b32_e32 v125, 0xffff0000, v218
	v_pk_add_f32 v[124:125], v[134:135], v[124:125]
	v_lshlrev_b32_e32 v126, 16, v219
	v_and_b32_e32 v127, 0xffff0000, v219
	v_lshl_add_u64 v[134:135], s[8:9], 0, v[132:133]
	v_pk_add_f32 v[126:127], v[136:137], v[126:127]
	v_pk_add_f32 v[128:129], v[128:129], v[138:139]
	s_waitcnt vmcnt(1)
	v_cvt_f32_f16_e32 v138, v220
	v_cvt_f32_f16_sdwa v139, v220 dst_sel:DWORD dst_unused:UNUSED_PAD src0_sel:WORD_1
	v_cvt_f32_f16_e32 v134, v221
	v_cvt_f32_f16_sdwa v135, v221 dst_sel:DWORD dst_unused:UNUSED_PAD src0_sel:WORD_1
	v_pk_mul_f32 v[138:139], v[138:139], s[4:5] op_sel_hi:[1,0]
	s_nop 0
	v_pk_fma_f32 v[96:97], v[96:97], s[6:7], v[138:139] op_sel_hi:[1,0,1]
	v_pk_mul_f32 v[134:135], v[134:135], s[4:5] op_sel_hi:[1,0]
	s_nop 0
	v_pk_fma_f32 v[98:99], v[98:99], s[6:7], v[134:135] op_sel_hi:[1,0,1]
	v_cvt_f32_f16_e32 v134, v222
	v_cvt_f32_f16_sdwa v135, v222 dst_sel:DWORD dst_unused:UNUSED_PAD src0_sel:WORD_1
	v_cvt_f32_f16_e32 v136, v223
	v_cvt_f32_f16_sdwa v137, v223 dst_sel:DWORD dst_unused:UNUSED_PAD src0_sel:WORD_1
	v_pk_mul_f32 v[134:135], v[134:135], s[4:5] op_sel_hi:[1,0]
	s_nop 0
	v_pk_fma_f32 v[134:135], v[92:93], s[6:7], v[134:135] op_sel_hi:[1,0,1]
	v_pk_mul_f32 v[136:137], v[136:137], s[4:5] op_sel_hi:[1,0]
	v_lshl_add_u64 v[92:93], s[0:1], 0, v[132:133]
	v_pk_fma_f32 v[136:137], v[94:95], s[6:7], v[136:137] op_sel_hi:[1,0,1]
	s_waitcnt vmcnt(0)
; __device__ __forceinline__ float h2f_(unsigned short b) { return (float)__builtin_bit_cast(_Float16, b); }
;     __device__ __forceinline__ void fused(Acc& acc, const Unit& u, int wr, int wc, int fr, int fq, LAS unsigned char* lds, int wid, int lane) const {
;     ...
;             for (int m = 0; m < 4; ++m) { const size_t off = (size_t)(u.pm * BM + ai * HALF + wr * 64 + m * 16 + fr) * 1024 + col0;
; #pragma unroll
;                 for (int bj = 0; bj < 2; ++bj) { const size_t o = off + bj * HALF; const u32x4 bw = *(const u32x4*)(xb + o);
;                     f32x4 v0 = (f32x4){h2f_((unsigned short)(bw.x & 0xffffu)), h2f_((unsigned short)(bw.x >> 16)), h2f_((unsigned short)(bw.y & 0xffffu)), h2f_((unsigned short)(bw.y >> 16))} * ALPHA + acc[ai][bj][m][0] * sc;
;                     f32x4 v1 = (f32x4){h2f_((unsigned short)(bw.z & 0xffffu)), h2f_((unsigned short)(bw.z >> 16)), h2f_((unsigned short)(bw.w & 0xffffu)), h2f_((unsigned short)(bw.w >> 16))} * ALPHA + acc[ai][bj][m][1] * sc;
;                     if (add) { const u32x4 av = *(const u32x4*)(add + o);
;                         v0[0] += __uint_as_float(av.x << 16); v0[1] += __uint_as_float(av.x & 0xffff0000u); v0[2] += __uint_as_float(av.y << 16); v0[3] += __uint_as_float(av.y & 0xffff0000u);
;                         v1[0] += __uint_as_float(av.z << 16); v1[1] += __uint_as_float(av.z & 0xffff0000u); v1[2] += __uint_as_float(av.w << 16); v1[3] += __uint_as_float(av.w & 0xffff0000u); }
;                     acc[ai][bj][m][0] = v0; acc[ai][bj][m][1] = v1; }
;                 asm volatile("" : "+v"(acc[ai][0][m][0]), "+v"(acc[ai][0][m][1]), "+v"(acc[ai][1][m][0]), "+v"(acc[ai][1][m][1]));
;                 if (m & 1) asm volatile("" ::: "memory"); }
	v_lshlrev_b32_e32 v132, 16, v242
	v_and_b32_e32 v133, 0xffff0000, v242
	v_pk_add_f32 v[96:97], v[96:97], v[132:133]
	v_add_u32_e32 v132, 0xa0, v190
	v_ashrrev_i32_e32 v133, 31, v132
	v_lshlrev_b32_e32 v92, 16, v243
	v_and_b32_e32 v93, 0xffff0000, v243
	v_lshlrev_b64 v[184:185], 10, v[132:133]
	v_pk_add_f32 v[98:99], v[98:99], v[92:93]
	v_lshlrev_b32_e32 v92, 16, v244
	v_and_b32_e32 v93, 0xffff0000, v244
	v_lshlrev_b32_e32 v94, 16, v245
	v_and_b32_e32 v95, 0xffff0000, v245
	v_lshl_add_u64 v[192:193], v[184:185], 0, v[164:165]
	v_pk_add_f32 v[92:93], v[134:135], v[92:93]
	v_pk_add_f32 v[94:95], v[136:137], v[94:95]
	v_lshlrev_b64 v[132:133], 1, v[192:193]
	v_lshl_add_u64 v[194:195], s[8:9], 0, v[132:133]
	global_load_dwordx4 v[134:137], v[194:195], off
	global_load_dwordx4 v[216:219], v132, s[0:1]
	global_load_dwordx4 v[220:223], v132, s[8:9] offset:256
	global_load_dwordx4 v[242:245], v132, s[0:1] offset:256
	s_waitcnt vmcnt(3)
	v_cvt_f32_f16_e32 v138, v134
	v_cvt_f32_f16_sdwa v139, v134 dst_sel:DWORD dst_unused:UNUSED_PAD src0_sel:WORD_1
	v_cvt_f32_f16_e32 v134, v135
	v_cvt_f32_f16_sdwa v135, v135 dst_sel:DWORD dst_unused:UNUSED_PAD src0_sel:WORD_1
	v_pk_mul_f32 v[138:139], v[138:139], s[4:5] op_sel_hi:[1,0]
	s_nop 0
	v_pk_fma_f32 v[120:121], v[120:121], s[6:7], v[138:139] op_sel_hi:[1,0,1]
	v_pk_mul_f32 v[134:135], v[134:135], s[4:5] op_sel_hi:[1,0]
	s_nop 0
	v_pk_fma_f32 v[122:123], v[122:123], s[6:7], v[134:135] op_sel_hi:[1,0,1]
	v_cvt_f32_f16_e32 v134, v136
	v_cvt_f32_f16_sdwa v135, v136 dst_sel:DWORD dst_unused:UNUSED_PAD src0_sel:WORD_1
	v_cvt_f32_f16_e32 v136, v137
	v_cvt_f32_f16_sdwa v137, v137 dst_sel:DWORD dst_unused:UNUSED_PAD src0_sel:WORD_1
	v_pk_mul_f32 v[134:135], v[134:135], s[4:5] op_sel_hi:[1,0]
	s_nop 0
	v_pk_fma_f32 v[134:135], v[116:117], s[6:7], v[134:135] op_sel_hi:[1,0,1]
	v_pk_mul_f32 v[136:137], v[136:137], s[4:5] op_sel_hi:[1,0]
	v_lshl_add_u64 v[116:117], s[0:1], 0, v[132:133]
	v_pk_fma_f32 v[136:137], v[118:119], s[6:7], v[136:137] op_sel_hi:[1,0,1]
	v_or_b32_e32 v132, 0x100, v132
	s_waitcnt vmcnt(2)
	v_lshlrev_b32_e32 v138, 16, v216
	v_and_b32_e32 v139, 0xffff0000, v216
	v_lshlrev_b32_e32 v116, 16, v217
	v_and_b32_e32 v117, 0xffff0000, v217
	v_pk_add_f32 v[122:123], v[122:123], v[116:117]
	v_lshlrev_b32_e32 v116, 16, v218
	v_and_b32_e32 v117, 0xffff0000, v218
	v_pk_add_f32 v[116:117], v[134:135], v[116:117]
	v_lshlrev_b32_e32 v118, 16, v219
	v_and_b32_e32 v119, 0xffff0000, v219
	v_lshl_add_u64 v[134:135], s[8:9], 0, v[132:133]
	v_pk_add_f32 v[118:119], v[136:137], v[118:119]
	v_pk_add_f32 v[120:121], v[120:121], v[138:139]
	s_waitcnt vmcnt(1)
	v_cvt_f32_f16_e32 v138, v220
	v_cvt_f32_f16_sdwa v139, v220 dst_sel:DWORD dst_unused:UNUSED_PAD src0_sel:WORD_1
	v_cvt_f32_f16_e32 v134, v221
	v_cvt_f32_f16_sdwa v135, v221 dst_sel:DWORD dst_unused:UNUSED_PAD src0_sel:WORD_1
	v_pk_mul_f32 v[138:139], v[138:139], s[4:5] op_sel_hi:[1,0]
	s_nop 0
	v_pk_fma_f32 v[104:105], v[104:105], s[6:7], v[138:139] op_sel_hi:[1,0,1]
	v_pk_mul_f32 v[134:135], v[134:135], s[4:5] op_sel_hi:[1,0]
	s_nop 0
	v_pk_fma_f32 v[106:107], v[106:107], s[6:7], v[134:135] op_sel_hi:[1,0,1]
	v_cvt_f32_f16_e32 v134, v222
	v_cvt_f32_f16_sdwa v135, v222 dst_sel:DWORD dst_unused:UNUSED_PAD src0_sel:WORD_1
	v_cvt_f32_f16_e32 v136, v223
	v_cvt_f32_f16_sdwa v137, v223 dst_sel:DWORD dst_unused:UNUSED_PAD src0_sel:WORD_1
	v_pk_mul_f32 v[134:135], v[134:135], s[4:5] op_sel_hi:[1,0]
	s_nop 0
	v_pk_fma_f32 v[134:135], v[100:101], s[6:7], v[134:135] op_sel_hi:[1,0,1]
	v_pk_mul_f32 v[136:137], v[136:137], s[4:5] op_sel_hi:[1,0]
	v_lshl_add_u64 v[100:101], s[0:1], 0, v[132:133]
	v_pk_fma_f32 v[136:137], v[102:103], s[6:7], v[136:137] op_sel_hi:[1,0,1]
	s_waitcnt vmcnt(0)
	v_lshlrev_b32_e32 v132, 16, v242
	v_and_b32_e32 v133, 0xffff0000, v242
	v_pk_add_f32 v[104:105], v[104:105], v[132:133]
	v_add_u32_e32 v132, 0xb0, v190
	v_ashrrev_i32_e32 v133, 31, v132
	v_lshlrev_b32_e32 v100, 16, v243
	v_and_b32_e32 v101, 0xffff0000, v243
	v_lshlrev_b64 v[190:191], 10, v[132:133]
	v_pk_add_f32 v[106:107], v[106:107], v[100:101]
	v_lshlrev_b32_e32 v100, 16, v244
	v_and_b32_e32 v101, 0xffff0000, v244
	v_lshlrev_b32_e32 v102, 16, v245
	v_and_b32_e32 v103, 0xffff0000, v245
	v_lshl_add_u64 v[206:207], v[190:191], 0, v[164:165]
	v_pk_add_f32 v[102:103], v[136:137], v[102:103]
	v_lshlrev_b64 v[136:137], 1, v[206:207]
	v_pk_add_f32 v[100:101], v[134:135], v[100:101]
	v_lshl_add_u64 v[208:209], s[8:9], 0, v[136:137]
	global_load_dwordx4 v[132:135], v[208:209], off
	global_load_dwordx4 v[216:219], v136, s[0:1]
	global_load_dwordx4 v[220:223], v136, s[8:9] offset:256
	global_load_dwordx4 v[242:245], v136, s[0:1] offset:256
	s_waitcnt vmcnt(3)
	v_cvt_f32_f16_e32 v138, v132
	v_cvt_f32_f16_sdwa v139, v132 dst_sel:DWORD dst_unused:UNUSED_PAD src0_sel:WORD_1
	v_cvt_f32_f16_e32 v132, v133
	v_cvt_f32_f16_sdwa v133, v133 dst_sel:DWORD dst_unused:UNUSED_PAD src0_sel:WORD_1
	v_pk_mul_f32 v[138:139], v[138:139], s[4:5] op_sel_hi:[1,0]
	s_nop 0
	v_pk_fma_f32 v[88:89], v[88:89], s[6:7], v[138:139] op_sel_hi:[1,0,1]
	v_pk_mul_f32 v[132:133], v[132:133], s[4:5] op_sel_hi:[1,0]
	s_nop 0
	v_pk_fma_f32 v[90:91], v[90:91], s[6:7], v[132:133] op_sel_hi:[1,0,1]
	v_cvt_f32_f16_e32 v132, v134
	v_cvt_f32_f16_sdwa v133, v134 dst_sel:DWORD dst_unused:UNUSED_PAD src0_sel:WORD_1
	v_cvt_f32_f16_e32 v134, v135
	v_cvt_f32_f16_sdwa v135, v135 dst_sel:DWORD dst_unused:UNUSED_PAD src0_sel:WORD_1
	v_pk_mul_f32 v[132:133], v[132:133], s[4:5] op_sel_hi:[1,0]
	s_nop 0
	v_pk_fma_f32 v[132:133], v[84:85], s[6:7], v[132:133] op_sel_hi:[1,0,1]
	v_pk_mul_f32 v[134:135], v[134:135], s[4:5] op_sel_hi:[1,0]
	v_lshl_add_u64 v[84:85], s[0:1], 0, v[136:137]
	v_pk_fma_f32 v[134:135], v[86:87], s[6:7], v[134:135] op_sel_hi:[1,0,1]
	v_or_b32_e32 v136, 0x100, v136
	s_waitcnt vmcnt(2)
;     __device__ __forceinline__ bool run(const f32x4 (&v)[2][2][4][2], const Unit& u, int wr, int wc, int fr, int fq, LAS unsigned char* lds, int wid, int lane) const {
;     ...
;                 float s = 0.f;
; #pragma unroll
;                 for (int bj = 0; bj < 2; ++bj)
; #pragma unroll
;                     for (int n = 0; n < 2; ++n) { const f32x4 x = v[ai][bj][m][n]; s += (x[0] + x[1]) + (x[2] + x[3]); }
;                 s += __shfl_xor(s, 16); s += __shfl_xor(s, 32);
;                 const float mw = s * (1.0f / 64.0f); float q = 0.f;
; #pragma unroll
;                 for (int bj = 0; bj < 2; ++bj)
; #pragma unroll
;                     for (int n = 0; n < 2; ++n) { const f32x4 d = v[ai][bj][m][n] - mw; q += (d[0] * d[0] + d[1] * d[1]) + (d[2] * d[2] + d[3] * d[3]); }
;                 q += __shfl_xor(q, 16); q += __shfl_xor(q, 32);
;     __device__ __forceinline__ void fused(Acc& acc, const Unit& u, int wr, int wc, int fr, int fq, LAS unsigned char* lds, int wid, int lane) const {
;     ...
;                 for (int bj = 0; bj < 2; ++bj) { const size_t o = off + bj * HALF; const u32x4 bw = *(const u32x4*)(xb + o);
;                     f32x4 v0 = (f32x4){h2f_((unsigned short)(bw.x & 0xffffu)), h2f_((unsigned short)(bw.x >> 16)), h2f_((unsigned short)(bw.y & 0xffffu)), h2f_((unsigned short)(bw.y >> 16))} * ALPHA + acc[ai][bj][m][0] * sc;
;                     f32x4 v1 = (f32x4){h2f_((unsigned short)(bw.z & 0xffffu)), h2f_((unsigned short)(bw.z >> 16)), h2f_((unsigned short)(bw.w & 0xffffu)), h2f_((unsigned short)(bw.w >> 16))} * ALPHA + acc[ai][bj][m][1] * sc;
;                     if (add) { const u32x4 av = *(const u32x4*)(add + o);
;                         v0[0] += __uint_as_float(av.x << 16); v0[1] += __uint_as_float(av.x & 0xffff0000u); v0[2] += __uint_as_float(av.y << 16); v0[3] += __uint_as_float(av.y & 0xffff0000u);
;                         v1[0] += __uint_as_float(av.z << 16); v1[1] += __uint_as_float(av.z & 0xffff0000u); v1[2] += __uint_as_float(av.w << 16); v1[3] += __uint_as_float(av.w & 0xffff0000u); }
;                     acc[ai][bj][m][0] = v0; acc[ai][bj][m][1] = v1; }
;                 asm volatile("" : "+v"(acc[ai][0][m][0]), "+v"(acc[ai][0][m][1]), "+v"(acc[ai][1][m][0]), "+v"(acc[ai][1][m][1]));
;                 if (m & 1) asm volatile("" ::: "memory"); }
	v_lshlrev_b32_e32 v138, 16, v216
	v_and_b32_e32 v139, 0xffff0000, v216
	v_lshlrev_b32_e32 v84, 16, v217
	v_and_b32_e32 v85, 0xffff0000, v217
	v_pk_add_f32 v[90:91], v[90:91], v[84:85]
	v_lshlrev_b32_e32 v84, 16, v218
	v_and_b32_e32 v85, 0xffff0000, v218
	v_pk_add_f32 v[84:85], v[132:133], v[84:85]
	v_lshlrev_b32_e32 v86, 16, v219
	v_and_b32_e32 v87, 0xffff0000, v219
	v_lshl_add_u64 v[132:133], s[8:9], 0, v[136:137]
	v_pk_add_f32 v[86:87], v[134:135], v[86:87]
	v_pk_add_f32 v[88:89], v[88:89], v[138:139]
	s_waitcnt vmcnt(1)
	v_cvt_f32_f16_e32 v138, v220
	v_cvt_f32_f16_sdwa v139, v220 dst_sel:DWORD dst_unused:UNUSED_PAD src0_sel:WORD_1
	v_cvt_f32_f16_e32 v132, v221
	v_cvt_f32_f16_sdwa v133, v221 dst_sel:DWORD dst_unused:UNUSED_PAD src0_sel:WORD_1
	v_pk_mul_f32 v[138:139], v[138:139], s[4:5] op_sel_hi:[1,0]
	s_nop 0
	v_pk_fma_f32 v[80:81], v[80:81], s[6:7], v[138:139] op_sel_hi:[1,0,1]
	v_pk_mul_f32 v[132:133], v[132:133], s[4:5] op_sel_hi:[1,0]
	v_mov_b32_e32 v138, v22
	v_pk_fma_f32 v[82:83], v[82:83], s[6:7], v[132:133] op_sel_hi:[1,0,1]
	v_cvt_f32_f16_e32 v132, v222
	v_cvt_f32_f16_sdwa v133, v222 dst_sel:DWORD dst_unused:UNUSED_PAD src0_sel:WORD_1
	v_cvt_f32_f16_e32 v134, v223
	v_cvt_f32_f16_sdwa v135, v223 dst_sel:DWORD dst_unused:UNUSED_PAD src0_sel:WORD_1
	v_mov_b32_e32 v139, v25
	v_pk_mul_f32 v[132:133], v[132:133], s[4:5] op_sel_hi:[1,0]
	v_pk_mul_f32 v[134:135], v[134:135], s[4:5] op_sel_hi:[1,0]
	v_pk_fma_f32 v[132:133], v[76:77], s[6:7], v[132:133] op_sel_hi:[1,0,1]
	v_lshl_add_u64 v[76:77], s[0:1], 0, v[136:137]
	v_pk_fma_f32 v[134:135], v[78:79], s[6:7], v[134:135] op_sel_hi:[1,0,1]
	s_lshl_b32 s0, s29, 3
	s_add_i32 s3, s24, s0
	s_waitcnt vmcnt(0)
	v_lshlrev_b32_e32 v136, 16, v242
	v_and_b32_e32 v137, 0xffff0000, v242
	v_lshlrev_b32_e32 v76, 16, v243
	v_and_b32_e32 v77, 0xffff0000, v243
	v_pk_add_f32 v[82:83], v[82:83], v[76:77]
	v_lshlrev_b32_e32 v76, 16, v244
	v_and_b32_e32 v77, 0xffff0000, v244
	v_pk_add_f32 v[76:77], v[132:133], v[76:77]
	v_and_b32_e32 v133, 64, v234
	v_xor_b32_e32 v132, 16, v234
	v_add_u32_e32 v133, 64, v133
	v_cmp_lt_i32_e32 vcc, v132, v133
	v_lshlrev_b32_e32 v78, 16, v245
	v_and_b32_e32 v79, 0xffff0000, v245
	v_cndmask_b32_e32 v132, v234, v132, vcc
	v_pk_add_f32 v[78:79], v[134:135], v[78:79]
	v_lshlrev_b32_e32 v134, 2, v132
	v_xor_b32_e32 v132, 32, v234
	v_cmp_lt_i32_e32 vcc, v132, v133
	v_pk_add_f32 v[80:81], v[80:81], v[136:137]
	v_mov_b32_e32 v133, v20
	v_cndmask_b32_e32 v132, v234, v132, vcc
	v_lshlrev_b32_e32 v135, 2, v132
	v_mov_b32_e32 v132, v19
	v_mov_b32_e32 v136, v18
	v_mov_b32_e32 v137, v21
	v_pk_add_f32 v[132:133], v[132:133], v[136:137]
	v_mov_b32_e32 v136, v23
	v_mov_b32_e32 v137, v24
	v_pk_add_f32 v[136:137], v[136:137], v[138:139]
	v_add_f32_e32 v132, v132, v133
	v_pk_add_f32 v[136:137], v[136:137], v[136:137] op_sel_hi:[0,1]
	v_add_f32_e32 v133, 0, v132
	v_add_f32_e32 v139, v6, v7
	v_mov_b32_e32 v138, v2
	v_mov_b32_e32 v136, v4
	v_mov_b32_e32 v132, v5
	v_pk_add_f32 v[138:139], v[138:139], v[140:141]
	v_pk_add_f32 v[132:133], v[136:137], v[132:133]
	v_cmp_gt_u32_e32 vcc, 16, v34
	v_pk_add_f32 v[132:133], v[138:139], v[132:133]
	s_nop 0
	v_add_f32_e32 v132, v132, v133
	ds_bpermute_b32 v133, v134, v132
	s_waitcnt lgkmcnt(0)
	v_add_f32_e32 v132, v132, v133
	ds_bpermute_b32 v133, v135, v132
	s_waitcnt lgkmcnt(0)
	v_add_f32_e32 v132, v132, v133
	v_fmamk_f32 v136, v132, 0xbc800000, v21
	v_fmamk_f32 v138, v132, 0xbc800000, v19
	v_fmamk_f32 v133, v132, 0xbc800000, v20
	v_fmamk_f32 v137, v132, 0xbc800000, v18
	v_mul_f32_e32 v138, v138, v138
	v_mul_f32_e32 v136, v136, v136
	v_fmac_f32_e32 v138, v137, v137
	v_fmac_f32_e32 v136, v133, v133
	v_fmamk_f32 v137, v132, 0xbc800000, v25
	v_fmamk_f32 v139, v132, 0xbc800000, v23
	v_add_f32_e32 v133, v138, v136
	v_fmamk_f32 v136, v132, 0xbc800000, v24
	v_fmamk_f32 v138, v132, 0xbc800000, v22
	v_mul_f32_e32 v139, v139, v139
	v_mul_f32_e32 v137, v137, v137
	v_fmac_f32_e32 v139, v138, v138
	v_fmac_f32_e32 v137, v136, v136
	v_add_f32_e32 v136, v139, v137
	v_fmamk_f32 v137, v132, 0xbc800000, v9
	v_fmamk_f32 v139, v132, 0xbc800000, v7
	v_add_f32_e32 v133, v133, v136
	v_fmamk_f32 v136, v132, 0xbc800000, v8
	v_fmamk_f32 v138, v132, 0xbc800000, v6
	v_mul_f32_e32 v139, v139, v139
	v_mul_f32_e32 v137, v137, v137
	v_fmac_f32_e32 v139, v138, v138
	v_fmac_f32_e32 v137, v136, v136
	v_add_f32_e32 v136, v139, v137
	v_fmamk_f32 v137, v132, 0xbc800000, v5
	v_fmamk_f32 v139, v132, 0xbc800000, v3
	v_add_f32_e32 v133, v136, v133
	v_fmamk_f32 v136, v132, 0xbc800000, v4
	v_fmamk_f32 v138, v132, 0xbc800000, v2
	v_mul_f32_e32 v139, v139, v139
	v_mul_f32_e32 v137, v137, v137
	v_fmac_f32_e32 v139, v138, v138
	v_fmac_f32_e32 v137, v136, v136
	v_add_f32_e32 v136, v139, v137
	v_add_f32_e32 v133, v136, v133
	ds_bpermute_b32 v136, v134, v133
	s_waitcnt lgkmcnt(0)
	v_add_f32_e32 v133, v133, v136
	ds_bpermute_b32 v136, v135, v133
	s_and_saveexec_b64 s[0:1], vcc
	s_cbranch_execz .LBB0_2259
	s_lshl_b32 s4, s28, 11
	s_add_i32 s4, s3, s4
	v_mul_f32_e32 v132, 0x3c800000, v132
	v_lshl_add_u32 v137, v210, 5, s4
	s_waitcnt lgkmcnt(0)
	v_add_f32_e32 v133, v133, v136
	ds_write_b64 v137, v[132:133]
